# v38 + attention unit prologue: accumulator init moved in front of the first-tile wait and barrier (runs under the load latency)
# speedup vs baseline: 1.0088x; 1.0063x over previous
; #define ATT_BAR() asm volatile("s_waitcnt lgkmcnt(0)\n\ts_barrier" ::: "memory")
; #define ATT_BAR() asm volatile("s_waitcnt vmcnt(0) lgkmcnt(0)\n\ts_barrier" ::: "memory")
; template <int DQK>
; __device__ __forceinline__ void attn_pass4(LAS unsigned char* lds, const bf16* Qp, int qpitch, const bf16* Kp, int kpitch, const bf16* Vp, int vpitch, int q0, f32x16 (&o)[4], float (&rl)[16]) {
;     ...
; #pragma unroll
;     for (int db = 0; db < 4; ++db)
; #pragma unroll
;         for (int r = 0; r < 16; ++r) o[db][r] = 0.f;
;     float mhat = 0.f, l = 0.f;
;     f32x16 negm;
; #pragma unroll
;     for (int r = 0; r < 16; ++r) negm[r] = 0.f;
;     ...
;     ATT_DMA(0, 0, 0); ATT_BAR();
.LBB0_619:
	s_andn2_b32 s5, s5, 63
	s_lshl_b32 s5, s5, 2
	s_add_i32 s8, s30, 0x100
	s_add_i32 s81, s5, 0
	v_and_b32_e32 v167, 63, v32
	s_add_i32 s81, s81, 0x13800
	s_lshr_b32 s31, s8, 6
	v_mul_u32_u24_e32 v35, 0x90, v34
	v_lshlrev_b32_e32 v36, 1, v32
	v_lshlrev_b32_e32 v37, 3, v32
	s_cmp_lt_i32 s3, 8
	s_mov_b64 s[70:71], -1
	v_cmp_gt_u32_e64 s[8:9], 32, v167
	v_add3_u32 v188, 0, v35, v168
	v_lshlrev_b32_e32 v190, 2, v180
	v_lshl_add_u32 v169, v34, 2, s81
	v_lshrrev_b32_e32 v192, 2, v32
	v_and_b32_e32 v184, 32, v36
	v_and_b32_e32 v186, 24, v37
	s_cbranch_scc0 .LBB0_642
	v_and_or_b32 v32, v192, 3, v190
	v_mad_u32_u24 v32, v32, s82, 0
	v_mov_b32_e32 v46, v33
	v_mov_b32_e32 v47, v33
	v_add3_u32 v194, v32, v184, v186
	v_mov_b32_e32 v32, v33
	v_mov_b32_e32 v34, v33
	v_mov_b32_e32 v35, v33
	v_mov_b32_e32 v36, v33
	v_mov_b32_e32 v37, v33
	v_mov_b32_e32 v38, v33
	v_mov_b32_e32 v39, v33
	v_mov_b32_e32 v40, v33
	v_mov_b32_e32 v41, v33
	v_mov_b32_e32 v42, v33
	v_mov_b32_e32 v43, v33
	v_mov_b32_e32 v44, v33
	v_mov_b32_e32 v45, v33
	v_mov_b64_e32 v[96:97], v[46:47]
	v_mov_b64_e32 v[80:81], v[46:47]
	v_mov_b64_e32 v[64:65], v[46:47]
	s_lshl_b32 s5, s3, 10
	v_mov_b32_e32 v196, 0
	v_mov_b64_e32 v[94:95], v[44:45]
	v_mov_b64_e32 v[92:93], v[42:43]
	v_mov_b64_e32 v[90:91], v[40:41]
	v_mov_b64_e32 v[88:89], v[38:39]
	v_mov_b64_e32 v[86:87], v[36:37]
	v_mov_b64_e32 v[84:85], v[34:35]
	v_mov_b64_e32 v[82:83], v[32:33]
	v_mov_b64_e32 v[78:79], v[44:45]
	v_mov_b64_e32 v[76:77], v[42:43]
	v_mov_b64_e32 v[74:75], v[40:41]
	v_mov_b64_e32 v[72:73], v[38:39]
	v_mov_b64_e32 v[70:71], v[36:37]
	v_mov_b64_e32 v[68:69], v[34:35]
	v_mov_b64_e32 v[66:67], v[32:33]
	v_mov_b64_e32 v[62:63], v[44:45]
	v_mov_b64_e32 v[60:61], v[42:43]
	v_mov_b64_e32 v[58:59], v[40:41]
	v_mov_b64_e32 v[56:57], v[38:39]
	v_mov_b64_e32 v[54:55], v[36:37]
	v_mov_b64_e32 v[52:53], v[34:35]
	v_mov_b64_e32 v[50:51], v[32:33]
	v_mov_b64_e32 v[48:49], v[46:47]
	s_add_i32 s26, s5, 0x4800
	s_or_b32 s27, s76, 31
	v_mov_b32_e32 v171, v33
	v_mov_b32_e32 v177, v33
	s_movk_i32 s80, 0x2000
	v_mov_b32_e32 v173, v33
	v_mov_b32_e32 v175, v33
	v_mov_b32_e32 v179, v33
	s_mov_b32 s24, 0
	s_mov_b32 s18, 63
	s_mov_b64 s[70:71], s[60:61]
	v_mov_b64_e32 v[46:47], v[44:45]
	v_mov_b64_e32 v[44:45], v[42:43]
	v_mov_b64_e32 v[42:43], v[40:41]
	v_mov_b64_e32 v[40:41], v[38:39]
	v_mov_b64_e32 v[38:39], v[36:37]
	v_mov_b64_e32 v[36:37], v[34:35]
	v_mov_b64_e32 v[34:35], v[32:33]
	v_mov_b32_e32 v182, 0
	s_mov_b32 s72, 0
	v_mov_b32_e32 v98, 0
	v_mov_b32_e32 v99, v196
	v_mov_b32_e32 v100, v196
	v_mov_b32_e32 v101, v196
	v_mov_b32_e32 v102, v196
	v_mov_b32_e32 v103, v196
	v_mov_b32_e32 v104, v196
	v_mov_b32_e32 v105, v196
	v_mov_b32_e32 v106, v196
	v_mov_b32_e32 v107, v196
	v_mov_b32_e32 v108, v196
	v_mov_b32_e32 v109, v196
	v_mov_b32_e32 v110, v196
	v_mov_b32_e32 v111, v196
	v_mov_b32_e32 v112, v196
	v_mov_b32_e32 v113, v196
	s_waitcnt vmcnt(0) lgkmcnt(0)
	s_barrier

; #define ATT_BAR() asm volatile("s_waitcnt lgkmcnt(0)\n\ts_barrier" ::: "memory")
; #define ATT_BAR() asm volatile("s_waitcnt vmcnt(0) lgkmcnt(0)\n\ts_barrier" ::: "memory")
; template <int DQK>
; __device__ __forceinline__ void attn_pass4(LAS unsigned char* lds, const bf16* Qp, int qpitch, const bf16* Kp, int kpitch, const bf16* Vp, int vpitch, int q0, f32x16 (&o)[4], float (&rl)[16]) {
;     ...
; #pragma unroll
;     for (int db = 0; db < 4; ++db)
; #pragma unroll
;         for (int r = 0; r < 16; ++r) o[db][r] = 0.f;
;     float mhat = 0.f, l = 0.f;
;     f32x16 negm;
; #pragma unroll
;     for (int r = 0; r < 16; ++r) negm[r] = 0.f;
;     ...
;     ATT_DMA(0, 0, 0); ATT_BAR();
.LBB0_819:
	s_andn2_b32 s3, s3, 63
	s_lshl_b32 s3, s3, 2
	s_add_i32 s81, s3, 0
	v_and_b32_e32 v167, 63, v32
	s_add_i32 s81, s81, 0x13800
	v_mul_u32_u24_e32 v35, 0x90, v34
	v_lshlrev_b32_e32 v36, 1, v32
	v_lshlrev_b32_e32 v37, 3, v32
	s_cmp_lt_i32 s80, 8
	s_mov_b64 s[70:71], -1
	v_cmp_gt_u32_e64 s[8:9], 32, v167
	v_add3_u32 v188, 0, v35, v168
	v_lshlrev_b32_e32 v190, 2, v180
	v_lshl_add_u32 v169, v34, 2, s81
	v_lshrrev_b32_e32 v192, 2, v32
	v_and_b32_e32 v184, 32, v36
	v_and_b32_e32 v186, 24, v37
	s_cbranch_scc0 .LBB0_842
	v_and_or_b32 v32, v192, 3, v190
	v_mad_u32_u24 v32, v32, s82, 0
	v_mov_b32_e32 v46, v33
	v_mov_b32_e32 v47, v33
	v_add3_u32 v194, v32, v184, v186
	v_mov_b32_e32 v32, v33
	v_mov_b32_e32 v34, v33
	v_mov_b32_e32 v35, v33
	v_mov_b32_e32 v36, v33
	v_mov_b32_e32 v37, v33
	v_mov_b32_e32 v38, v33
	v_mov_b32_e32 v39, v33
	v_mov_b32_e32 v40, v33
	v_mov_b32_e32 v41, v33
	v_mov_b32_e32 v42, v33
	v_mov_b32_e32 v43, v33
	v_mov_b32_e32 v44, v33
	v_mov_b32_e32 v45, v33
	v_mov_b64_e32 v[96:97], v[46:47]
	v_mov_b64_e32 v[80:81], v[46:47]
	v_mov_b64_e32 v[64:65], v[46:47]
	s_lshl_b32 s3, s80, 10
	v_mov_b32_e32 v196, 0
	v_mov_b64_e32 v[94:95], v[44:45]
	v_mov_b64_e32 v[92:93], v[42:43]
	v_mov_b64_e32 v[90:91], v[40:41]
	v_mov_b64_e32 v[88:89], v[38:39]
	v_mov_b64_e32 v[86:87], v[36:37]
	v_mov_b64_e32 v[84:85], v[34:35]
	v_mov_b64_e32 v[82:83], v[32:33]
	v_mov_b64_e32 v[78:79], v[44:45]
	v_mov_b64_e32 v[76:77], v[42:43]
	v_mov_b64_e32 v[74:75], v[40:41]
	v_mov_b64_e32 v[72:73], v[38:39]
	v_mov_b64_e32 v[70:71], v[36:37]
	v_mov_b64_e32 v[68:69], v[34:35]
	v_mov_b64_e32 v[66:67], v[32:33]
	v_mov_b64_e32 v[62:63], v[44:45]
	v_mov_b64_e32 v[60:61], v[42:43]
	v_mov_b64_e32 v[58:59], v[40:41]
	v_mov_b64_e32 v[56:57], v[38:39]
	v_mov_b64_e32 v[54:55], v[36:37]
	v_mov_b64_e32 v[52:53], v[34:35]
	v_mov_b64_e32 v[50:51], v[32:33]
	v_mov_b64_e32 v[48:49], v[46:47]
	s_add_i32 s5, s3, 0x4800
	s_or_b32 s26, s76, 31
	v_mov_b32_e32 v171, v33
	v_mov_b32_e32 v177, v33
	s_movk_i32 s27, 0x2000
	v_mov_b32_e32 v173, v33
	v_mov_b32_e32 v175, v33
	v_mov_b32_e32 v179, v33
	s_mov_b32 s35, 0
	s_mov_b32 s18, 63
	s_mov_b64 s[70:71], s[62:63]
	v_mov_b64_e32 v[46:47], v[44:45]
	v_mov_b64_e32 v[44:45], v[42:43]
	v_mov_b64_e32 v[42:43], v[40:41]
	v_mov_b64_e32 v[40:41], v[38:39]
	v_mov_b64_e32 v[38:39], v[36:37]
	v_mov_b64_e32 v[36:37], v[34:35]
	v_mov_b64_e32 v[34:35], v[32:33]
	v_mov_b32_e32 v182, 0
	s_mov_b32 s72, 0
	v_mov_b32_e32 v98, 0
	v_mov_b32_e32 v99, v196
	v_mov_b32_e32 v100, v196
	v_mov_b32_e32 v101, v196
	v_mov_b32_e32 v102, v196
	v_mov_b32_e32 v103, v196
	v_mov_b32_e32 v104, v196
	v_mov_b32_e32 v105, v196
	v_mov_b32_e32 v106, v196
	v_mov_b32_e32 v107, v196
	v_mov_b32_e32 v108, v196
	v_mov_b32_e32 v109, v196
	v_mov_b32_e32 v110, v196
	v_mov_b32_e32 v111, v196
	v_mov_b32_e32 v112, v196
	v_mov_b32_e32 v113, v196
	s_waitcnt vmcnt(0) lgkmcnt(0)
	s_barrier
